# cooperative grid sync moved to the end of P0 (replaces XCD barrier 1) + XCD-local seams (3us stagger) + P4/P6' epilogue rewrites
# baseline (speedup 1.0000x reference)
.LBB0_2:
	s_or_b64 exec, exec, s[4:5]
	s_waitcnt lgkmcnt(0)
	v_writelane_b32 v255, s0, 1
	v_writelane_b32 v255, s1, 2
	s_add_u32 s36, s66, 0x40000
	s_addc_u32 s37, s67, 0
	s_lshl_b32 s78, s2, 9
	v_add_u32_e32 v64, s78, v66
	s_movk_i32 s6, 0xd80
	s_getreg_b32 s20, hwreg(HW_REG_XCC_ID, 0, 4)
	v_cmp_gt_i32_e64 s[4:5], s6, v64
	s_and_saveexec_b64 s[10:11], s[4:5]
	s_cbranch_execz .LBB0_10
	s_lshl_b32 s12, s3, 9
	v_cvt_f32_u32_e32 v1, s12
	v_add_u32_e32 v65, s12, v64
	v_mov_b32_e32 v2, s12
	v_cmp_gt_i32_e64 s[4:5], s6, v65
	v_rcp_iflag_f32_e32 v1, v1
	s_sub_i32 s13, 0, s12
	v_max_i32_e32 v3, 0xd80, v65
	v_addc_co_u32_e64 v2, s[6:7], v64, v2, s[4:5]
	v_mul_f32_e32 v1, 0x4f7ffffe, v1
	v_cvt_u32_f32_e32 v1, v1
	v_sub_u32_e32 v2, v3, v2
	s_mov_b64 s[14:15], -1
	v_mul_lo_u32 v3, s13, v1
	v_mul_hi_u32 v3, v1, v3
	v_add_u32_e32 v1, v1, v3
	v_mul_hi_u32 v1, v2, v1
	v_mul_lo_u32 v3, v1, s12
	v_sub_u32_e32 v2, v2, v3
	v_add_u32_e32 v4, 1, v1
	v_cmp_le_u32_e64 s[6:7], s12, v2
	v_subrev_u32_e32 v3, s12, v2
	s_nop 0
	v_cndmask_b32_e64 v1, v1, v4, s[6:7]
	v_cndmask_b32_e64 v2, v2, v3, s[6:7]
	v_add_u32_e32 v3, 1, v1
	v_cmp_le_u32_e64 s[6:7], s12, v2
	v_mov_b32_e32 v2, v64
	s_nop 0
	v_cndmask_b32_e64 v1, v1, v3, s[6:7]
	v_addc_co_u32_e64 v1, s[4:5], 1, v1, s[4:5]
	v_cmp_lt_u32_e64 s[4:5], 1, v1
	s_and_saveexec_b64 s[6:7], s[4:5]
	s_cbranch_execz .LBB0_7
	v_and_b32_e32 v4, -2, v1
	s_lshl_b32 s13, s3, 10
	s_mov_b32 s16, s13
	s_mov_b64 s[14:15], 0
	v_mov_b32_e32 v5, 0
	v_mov_b32_e32 v6, v4
	v_mov_b64_e32 v[2:3], v[64:65]

.LBB0_10:
	s_or_b64 exec, exec, s[10:11]
	s_load_dwordx16 s[4:19], s[0:1], 0x0
	s_and_b32 s0, s20, 15
	v_writelane_b32 v254, s0, 0
	s_waitcnt lgkmcnt(0)
	s_movk_i32 s0, 0x4000
	s_lshl_b32 s44, s3, 9
	v_cmp_gt_i32_e32 vcc, s0, v64
	s_and_saveexec_b64 s[0:1], vcc
	s_cbranch_execz .LBB0_32
	v_ashrrev_i32_e32 v65, 31, v64
	s_ashr_i32 s45, s44, 31
	v_lshlrev_b64 v[0:1], 2, v[64:65]
	s_lshl_b64 s[34:35], s[44:45], 2
	s_mov_b64 s[38:39], 0
	v_mov_b32_e32 v4, 0
	s_movk_i32 s20, 0x2000
	s_movk_i32 s21, 0x800
	s_mov_b32 s22, 0x60000
	s_movk_i32 s23, 0x1000
	s_movk_i32 s24, 0x3fff
	s_mov_b64 s[40:41], s[80:81]
	s_mov_b64 s[42:43], s[6:7]
	s_mov_b64 s[46:47], s[66:67]
	v_mov_b32_e32 v5, v64
	s_branch .LBB0_26

.LBB0_58:
	s_or_b64 exec, exec, s[0:1]
	v_mbcnt_lo_u32_b32 v0, -1, 0
	v_mbcnt_hi_u32_b32 v0, -1, v0
	s_waitcnt vmcnt(0)
	s_and_b32 s0, s26, 0xffffffc0
	v_sub_u32_e32 v0, 0, v0
	v_cmp_eq_u32_e32 vcc, s0, v0
	s_barrier
	v_writelane_b32 v254, s0, 6
	s_and_saveexec_b64 s[0:1], vcc
	v_writelane_b32 v254, s64, 7
	s_nop 1
	v_writelane_b32 v254, s65, 8
	v_writelane_b32 v254, s66, 9
	v_writelane_b32 v254, s67, 10
	v_writelane_b32 v254, s42, 11
	v_writelane_b32 v254, s43, 12
	s_cbranch_execz .LBB0_110
	v_readlane_b32 s46, v255, 1
	v_readlane_b32 s47, v255, 2
	s_nop 3
	s_add_u32 s46, s46, 0x70
	s_addc_u32 s47, s47, 0
	buffer_wbl2 sc1
	s_waitcnt vmcnt(0)
	s_load_dwordx2 s[46:47], s[46:47], 0x58
	v_mov_b32_e32 v2, 0
	s_mov_b64 s[10:11], exec
	v_mbcnt_lo_u32_b32 v1, s10, 0
	v_mbcnt_hi_u32_b32 v1, s11, v1
	s_waitcnt lgkmcnt(0)
	global_load_dword v0, v2, s[46:47] offset:40
	v_cmp_eq_u32_e64 s[4:5], 0, v1
	s_and_saveexec_b64 s[48:49], s[4:5]
	s_cbranch_execz .Lcg_13
	s_bcnt1_i32_b64 s4, s[10:11]
	v_mov_b32_e32 v3, s4
	global_atomic_add v3, v2, v3, s[46:47] offset:32 sc0
.Lcg_13:
	s_or_b64 exec, exec, s[48:49]
	s_waitcnt vmcnt(0)
	v_readfirstlane_b32 s4, v3
	v_add_u32_e32 v2, -1, v0
	s_nop 0
	v_add_u32_e32 v1, s4, v1
	v_cmp_eq_u32_sdwa s[4:5], v1, v2 src0_sel:WORD_0 src1_sel:DWORD
	s_and_saveexec_b64 s[10:11], s[4:5]
	s_cbranch_execz .Lcg_16
	s_mov_b64 s[48:49], exec
	v_mbcnt_lo_u32_b32 v2, s48, 0
	v_mbcnt_hi_u32_b32 v2, s49, v2
	v_cmp_eq_u32_e64 s[4:5], 0, v2
	s_and_b64 s[4:5], exec, s[4:5]
	s_mov_b64 exec, s[4:5]
	s_cbranch_execz .Lcg_16
	v_sub_u32_e32 v0, 0x10000, v0
	s_bcnt1_i32_b64 s4, s[48:49]
	v_mul_lo_u32 v0, v0, s4
	v_mov_b32_e32 v2, 0
	global_atomic_add v2, v0, s[46:47] offset:32
.Lcg_16:
	s_or_b64 exec, exec, s[10:11]
	v_mov_b32_e32 v0, 0
	global_load_dword v2, v0, s[46:47] offset:32 sc1
	v_and_b32_e32 v1, 0xffff0000, v1
	s_waitcnt vmcnt(0)
	v_and_b32_e32 v2, 0xffff0000, v2
	v_cmp_eq_u32_e64 s[4:5], v2, v1
	s_and_b64 exec, exec, s[4:5]
	s_cbranch_execz .Lcg_19
	s_mov_b64 s[10:11], 0
.Lcg_18:
	s_sleep 1
	global_load_dword v2, v0, s[46:47] offset:32 sc1
	s_waitcnt vmcnt(0)
	v_and_b32_e32 v2, 0xffff0000, v2
	v_cmp_ne_u32_e64 s[4:5], v2, v1
	s_or_b64 s[10:11], s[4:5], s[10:11]
	s_andn2_b64 exec, exec, s[10:11]
	s_cbranch_execnz .Lcg_18
.Lcg_19:
	buffer_inv sc1
	s_mov_b64 exec, 1
	s_waitcnt vmcnt(0)
	v_readlane_b32 s20, v254, 0
	s_nop 3
	s_lshl_b32 s21, s20, 8
	v_mov_b32_e32 v0, s21
	v_mov_b32_e32 v1, 1
	global_atomic_add v0, v1, s[36:37] offset:1024
	s_and_b32 s21, s2, 7
	s_lshl_b32 s21, s21, 2
	s_lshl_b32 s20, 1, s20
	v_mov_b32_e32 v0, s21
	v_mov_b32_e32 v1, s20
	global_atomic_or v0, v1, s[36:37] offset:32
	s_waitcnt vmcnt(0)
	s_branch .LBB0_110

.LBB0_436:
	v_mbcnt_lo_u32_b32 v0, -1, 0
	v_mbcnt_hi_u32_b32 v0, -1, v0
	s_waitcnt vmcnt(0)
	v_readlane_b32 s4, v254, 6
	v_sub_u32_e32 v0, 0, v0
	s_waitcnt lgkmcnt(0)
	v_cmp_eq_u32_e32 vcc, s4, v0
	s_barrier
	s_and_saveexec_b64 s[4:5], vcc
	s_cbranch_execz .LBB0_488
	v_readlane_b32 s6, v255, 0
	s_nop 3
	s_cmp_eq_u32 s6, 0
	s_cbranch_scc1 .Lxl_b4_global
	v_mov_b32_e32 v0, 0x20400
	ds_read_b32 v2, v0
	v_readlane_b32 s6, v254, 0
	s_nop 3
	s_lshl_b32 s6, s6, 8
	s_add_u32 s6, s6, 0x40000
	s_add_u32 s6, s66, s6
	s_addc_u32 s7, s67, 0
	v_mov_b32_e32 v3, 0x1400
	v_mov_b32_e32 v4, 1
	s_waitcnt lgkmcnt(0)
	v_readfirstlane_b32 s8, v2
	global_atomic_add v5, v3, v4, s[6:7] sc0
	s_mul_i32 s10, s8, 3
	s_waitcnt vmcnt(0)
	v_readfirstlane_b32 s9, v5
	s_add_i32 s9, s9, 1
	v_mov_b32_e32 v3, 0x2400
	s_cmp_eq_u32 s9, s10
	s_cbranch_scc0 .Lxl_b4_wait
	global_atomic_add v3, v4, s[6:7]
	s_branch .Lxl_b4_acq

.Lxl_b4_spin:
	s_sleep 1
	global_load_dword v5, v3, s[6:7] sc1
	s_waitcnt vmcnt(0)
	v_readfirstlane_b32 s9, v5
	s_cmp_lg_u32 s9, 2
	s_cbranch_scc1 .Lxl_b4_acq
	s_add_i32 s11, s11, 1
	s_cmp_lt_u32 s11, 2000
	s_cbranch_scc1 .Lxl_b4_spin

.LBB0_514:
	v_mbcnt_lo_u32_b32 v0, -1, 0
	v_mbcnt_hi_u32_b32 v0, -1, v0
	s_waitcnt vmcnt(0)
	v_readlane_b32 s4, v254, 6
	v_sub_u32_e32 v0, 0, v0
	s_waitcnt vmcnt(0)
	v_cmp_eq_u32_e32 vcc, s4, v0
	s_barrier
	s_and_saveexec_b64 s[4:5], vcc
	s_cbranch_execz .LBB0_566
	v_readlane_b32 s6, v255, 0
	s_nop 3
	s_cmp_eq_u32 s6, 0
	s_cbranch_scc1 .Lxl_b5_global
	v_mov_b32_e32 v0, 0x20400
	ds_read_b32 v2, v0
	v_readlane_b32 s6, v254, 0
	s_nop 3
	s_lshl_b32 s6, s6, 8
	s_add_u32 s6, s6, 0x40000
	s_add_u32 s6, s66, s6
	s_addc_u32 s7, s67, 0
	v_mov_b32_e32 v3, 0x1400
	v_mov_b32_e32 v4, 1
	s_waitcnt lgkmcnt(0)
	v_readfirstlane_b32 s8, v2
	global_atomic_add v5, v3, v4, s[6:7] sc0
	s_mul_i32 s10, s8, 4
	s_waitcnt vmcnt(0)
	v_readfirstlane_b32 s9, v5
	s_add_i32 s9, s9, 1
	v_mov_b32_e32 v3, 0x2400
	s_cmp_eq_u32 s9, s10
	s_cbranch_scc0 .Lxl_b5_wait
	global_atomic_add v3, v4, s[6:7]
	s_branch .Lxl_b5_acq
